# final norm loop (phase 14): mid-row waits on the next row's prefetch replaced by one wait before the first rotation copy
# speedup vs baseline: 1.0016x; 1.0016x over previous
; __device__ __forceinline__ void norm_phase(const float* lat, const float* ctxp, const bf16_t* dbuf, const bf16_t* dbuf2, const bf16_t* dpart, float* xout, int nrows, const float* gw, const float* mod, int shift_off, int scale_off, bf16_t* outb, float* outf) {
;     const int wid = threadIdx.x >> 6, lane = threadIdx.x & 63;
;     const int nw = gridDim.x * 8, gwv = blockIdx.x * 8 + wid, per = (nrows + nw - 1) / nw;
;     const int rb = gwv * per, re = (rb + per < nrows) ? rb + per : nrows;
;     if (rb >= re) return;
;     int cur_b = -1;
;     f32x4 ca[8], cb[8], v[8]; u32x2 dv[8], dw[8];
;     { const float* src = rb < ML ? lat + (size_t)rb * D : ctxp + (size_t)(rb - ML) * D;
; #pragma unroll
;       for (int i = 0; i < 8; ++i) { v[i] = __builtin_nontemporal_load((const f32x4*)(src + i * 256 + lane * 4)); dv[i] = (u32x2){0u, 0u}; if (dbuf && !dpart) dv[i] = *(const u32x2*)(dbuf + (size_t)rb * D + i * 256 + lane * 4);
;           dw[i] = (u32x2){0u, 0u}; if (dbuf2) dw[i] = __builtin_nontemporal_load((const u32x2*)(dbuf2 + (size_t)rb * D + i * 256 + lane * 4)); } }
.LBB0_1889:
	s_cmp_lt_i32 s76, 15
	s_cselect_b64 s[0:1], -1, 0
	s_cmp_gt_i32 s77, 14
	s_cselect_b64 s[4:5], -1, 0
	s_and_b64 s[0:1], s[0:1], s[4:5]
	s_andn2_b64 vcc, exec, s[0:1]
	s_cbranch_vccnz .LBB0_1951
	s_lshl_b32 s0, s78, 3
	s_abs_i32 s1, s0
	s_waitcnt vmcnt(0)
	v_cvt_f32_u32_e32 v0, s1
	v_lshl_add_u32 v1, s2, 3, v244
	s_add_i32 s2, s0, 0x7fff
	s_sub_i32 s3, 0xffff8001, s0
	v_rcp_iflag_f32_e32 v0, v0
	s_xor_b32 s0, s2, s0
	s_max_i32 s2, s2, s3
	s_sub_i32 s3, 0, s1
	v_mul_f32_e32 v0, 0x4f7ffffe, v0
	v_cvt_u32_f32_e32 v0, v0
	s_ashr_i32 s0, s0, 31
	v_readfirstlane_b32 s4, v0
	s_mul_i32 s3, s3, s4
	s_mul_hi_u32 s3, s4, s3
	s_add_i32 s4, s4, s3
	s_mul_hi_u32 s3, s2, s4
	s_mul_i32 s4, s3, s1
	s_sub_i32 s2, s2, s4
	s_add_i32 s5, s3, 1
	s_sub_i32 s4, s2, s1
	s_cmp_ge_u32 s2, s1
	s_cselect_b32 s3, s5, s3
	s_cselect_b32 s2, s4, s2
	s_add_i32 s4, s3, 1
	s_cmp_ge_u32 s2, s1
	s_cselect_b32 s1, s4, s3
	s_xor_b32 s1, s1, s0
	s_sub_i32 s0, s1, s0
	v_mul_lo_u32 v96, s0, v1
	v_add_u32_e32 v0, s0, v96
	v_min_i32_e32 v178, 0x8000, v0
	v_cmp_lt_i32_e32 vcc, v96, v178
	s_and_saveexec_b64 s[2:3], vcc
	s_cbranch_execz .LBB0_1897
	v_ashrrev_i32_e32 v97, 31, v96
	v_lshlrev_b32_e32 v4, 2, v140
	v_and_b32_e32 v8, 0xfc, v4
	v_mov_b32_e32 v98, 0
	v_lshlrev_b64 v[6:7], 12, v[96:97]
	v_lshlrev_b32_e32 v4, 2, v8
	v_lshlrev_b32_e32 v8, 1, v8
	v_mov_b32_e32 v9, v98
	v_lshl_add_u64 v[10:11], s[74:75], 0, v[6:7]
	v_lshl_add_u64 v[8:9], v[10:11], 0, v[8:9]
	s_mov_b64 s[0:1], 0xa1a2000
	v_lshl_add_u64 v[10:11], v[8:9], 0, s[0:1]
	s_mov_b64 s[0:1], 0x32fa4000
	v_lshl_add_u64 v[12:13], v[8:9], 0, s[0:1]
	s_mov_b32 s0, 0xa1a2000
	v_add_co_u32_e32 v14, vcc, s0, v8
	v_lshlrev_b64 v[0:1], 13, v[96:97]
	s_nop 0
	v_addc_co_u32_e32 v15, vcc, 0, v9, vcc
	s_mov_b32 s0, 0x32fa4000
	v_lshl_add_u64 v[2:3], s[72:73], 0, v[0:1]
	v_mov_b32_e32 v5, v98
	v_add_co_u32_e32 v8, vcc, s0, v8
	v_lshl_add_u64 v[2:3], v[2:3], 0, v[4:5]
	s_nop 0
	v_addc_co_u32_e32 v9, vcc, 0, v9, vcc
	s_movk_i32 s10, 0x1000
	global_load_dwordx4 v[60:63], v[2:3], off nt
	global_load_dwordx4 v[56:59], v[2:3], off offset:1024 nt
	global_load_dwordx4 v[52:55], v[2:3], off offset:2048 nt
	global_load_dwordx4 v[48:51], v[2:3], off offset:3072 nt
	v_add_co_u32_e32 v2, vcc, s10, v2
	v_readlane_b32 s12, v254, 18
	s_nop 0
	v_addc_co_u32_e32 v3, vcc, 0, v3, vcc
	global_load_dwordx2 v[138:139], v[10:11], off offset:512
	global_load_dwordx2 v[134:135], v[10:11], off offset:1024
	global_load_dwordx2 v[130:131], v[10:11], off offset:1536
	global_load_dwordx2 v[126:127], v[10:11], off offset:2048
	global_load_dwordx4 v[44:47], v[2:3], off nt
	global_load_dwordx4 v[40:43], v[2:3], off offset:1024 nt
	global_load_dwordx2 v[136:137], v[12:13], off offset:1024 nt
	global_load_dwordx2 v[132:133], v[12:13], off offset:1536 nt
	global_load_dwordx2 v[128:129], v[12:13], off offset:2048 nt
	global_load_dwordx2 v[122:123], v[12:13], off offset:2560 nt
	global_load_dwordx4 v[36:39], v[2:3], off offset:2048 nt
	global_load_dwordx4 v[32:35], v[2:3], off offset:3072 nt
	global_load_dwordx2 v[142:143], v[12:13], off offset:512 nt
	global_load_dwordx2 v[124:125], v[10:11], off offset:2560
	global_load_dwordx2 v[118:119], v[10:11], off offset:3072
	global_load_dwordx2 v[114:115], v[10:11], off offset:3584
	global_load_dwordx2 v[144:145], v[14:15], off
	global_load_dwordx2 v[146:147], v[8:9], off nt
	global_load_dwordx2 v[120:121], v[12:13], off offset:3072 nt
	global_load_dwordx2 v[116:117], v[12:13], off offset:3584 nt
	v_readlane_b32 s14, v254, 20
	v_readlane_b32 s15, v254, 21
	v_readlane_b32 s26, v254, 32
	v_readlane_b32 s27, v254, 33
	s_mov_b64 s[14:15], s[26:27]
	v_or_b32_e32 v2, 0x1000, v4
	v_mov_b32_e32 v3, v98
	v_lshl_add_u64 v[102:103], s[14:15], 0, v[2:3]
	v_or_b32_e32 v2, 0x1400, v4
	v_lshl_add_u64 v[104:105], s[14:15], 0, v[2:3]
	v_or_b32_e32 v2, 0x1800, v4
	v_lshl_add_u64 v[106:107], s[14:15], 0, v[2:3]
	v_or_b32_e32 v2, 0x1c00, v4
	v_lshl_add_u64 v[108:109], s[14:15], 0, v[2:3]
	v_mbcnt_lo_u32_b32 v2, -1, 0
	v_mbcnt_hi_u32_b32 v2, -1, v2
	v_and_b32_e32 v3, 64, v2
	v_lshl_add_u64 v[100:101], s[14:15], 0, v[4:5]
	v_add_u32_e32 v3, 64, v3
	v_xor_b32_e32 v4, 32, v2
	v_cmp_lt_i32_e32 vcc, v4, v3
	s_mov_b64 s[0:1], 0x32fa5000
	v_mov_b32_e32 v181, -1
	v_cndmask_b32_e32 v4, v2, v4, vcc
	v_lshlrev_b32_e32 v97, 2, v4
	v_xor_b32_e32 v4, 16, v2
	v_cmp_lt_i32_e32 vcc, v4, v3
	s_mov_b64 s[4:5], 0
	v_mov_b32_e32 v185, 0x358637bd
	v_cndmask_b32_e32 v4, v2, v4, vcc
	v_lshlrev_b32_e32 v179, 2, v4
	v_xor_b32_e32 v4, 8, v2
	v_cmp_lt_i32_e32 vcc, v4, v3
	s_mov_b32 s11, 0x800000
	s_mov_b64 s[6:7], 0x2000
	v_cndmask_b32_e32 v4, v2, v4, vcc
	v_lshlrev_b32_e32 v180, 2, v4
	v_xor_b32_e32 v4, 4, v2
	v_cmp_lt_i32_e32 vcc, v4, v3
	s_mov_b64 s[8:9], 0x1000
	v_readlane_b32 s13, v254, 19
	v_cndmask_b32_e32 v4, v2, v4, vcc
	v_lshlrev_b32_e32 v182, 2, v4
	v_xor_b32_e32 v4, 2, v2
	v_cmp_lt_i32_e32 vcc, v4, v3
	v_readlane_b32 s16, v254, 22
	v_readlane_b32 s17, v254, 23
	v_cndmask_b32_e32 v4, v2, v4, vcc
	v_lshlrev_b32_e32 v183, 2, v4
	v_xor_b32_e32 v4, 1, v2
	v_cmp_lt_i32_e32 vcc, v4, v3
	v_readlane_b32 s18, v254, 24
	v_readlane_b32 s19, v254, 25
	v_cndmask_b32_e32 v2, v2, v4, vcc
	v_lshlrev_b32_e32 v184, 2, v2
	v_and_b32_e32 v2, 63, v140
	v_lshl_or_b32 v0, v2, 4, v0
	v_lshl_or_b32 v6, v2, 3, v6
	v_lshl_add_u64 v[110:111], s[72:73], 0, v[0:1]
	v_lshl_add_u64 v[0:1], s[74:75], 0, v[6:7]
	v_lshl_add_u64 v[112:113], v[0:1], 0, s[0:1]
	v_readlane_b32 s20, v254, 26
	v_readlane_b32 s21, v254, 27
	v_readlane_b32 s22, v254, 28
	v_readlane_b32 s23, v254, 29
	v_readlane_b32 s24, v254, 30
	v_readlane_b32 s25, v254, 31
	s_waitcnt vmcnt(0)
	s_branch .LBB0_1893
; __device__ __forceinline__ float bflo(unsigned u) { return __uint_as_float(u << 16); }
; __device__ __forceinline__ float bfhi(unsigned u) { return __uint_as_float(u & 0xffff0000u); }
; __device__ __forceinline__ void norm_phase(const float* lat, const float* ctxp, const bf16_t* dbuf, const bf16_t* dbuf2, const bf16_t* dpart, float* xout, int nrows, const float* gw, const float* mod, int shift_off, int scale_off, bf16_t* outb, float* outf) {
;     ...
;         float ss = 0.f;
; #pragma unroll
;         for (int i = 0; i < 8; ++i) {
;             v[i][0] += bflo(dv[i].x) + bflo(dw[i].x); v[i][1] += bfhi(dv[i].x) + bfhi(dw[i].x); v[i][2] += bflo(dv[i].y) + bflo(dw[i].y); v[i][3] += bfhi(dv[i].y) + bfhi(dw[i].y);
;             ss += v[i][0] * v[i][0] + v[i][1] * v[i][1] + v[i][2] * v[i][2] + v[i][3] * v[i][3]; }
;         ss = wave_sum(ss);
.LBB0_1892:
	s_or_b64 exec, exec, s[0:1]
	v_lshlrev_b32_e32 v186, 16, v144
	v_and_b32_e32 v187, 0xffff0000, v144
	v_lshlrev_b32_e32 v188, 16, v146
	v_and_b32_e32 v189, 0xffff0000, v146
	v_pk_add_f32 v[186:187], v[186:187], v[188:189]
	v_lshlrev_b32_e32 v188, 16, v142
	v_pk_add_f32 v[60:61], v[60:61], v[186:187]
	v_lshlrev_b32_e32 v186, 16, v138
	v_and_b32_e32 v187, 0xffff0000, v138
	v_and_b32_e32 v189, 0xffff0000, v142
	v_pk_add_f32 v[186:187], v[186:187], v[188:189]
	v_lshlrev_b32_e32 v188, 16, v136
	v_pk_add_f32 v[56:57], v[186:187], v[56:57]
	v_lshlrev_b32_e32 v186, 16, v134
	v_and_b32_e32 v187, 0xffff0000, v134
	v_and_b32_e32 v189, 0xffff0000, v136
	v_pk_add_f32 v[186:187], v[186:187], v[188:189]
	v_lshlrev_b32_e32 v188, 16, v132
	v_pk_add_f32 v[52:53], v[186:187], v[52:53]
	v_lshlrev_b32_e32 v186, 16, v130
	v_and_b32_e32 v187, 0xffff0000, v130
	v_and_b32_e32 v189, 0xffff0000, v132
	v_pk_add_f32 v[186:187], v[186:187], v[188:189]
	v_lshlrev_b32_e32 v188, 16, v128
	v_pk_add_f32 v[48:49], v[186:187], v[48:49]
	v_lshlrev_b32_e32 v186, 16, v126
	v_and_b32_e32 v187, 0xffff0000, v126
	v_and_b32_e32 v189, 0xffff0000, v128
	v_lshlrev_b32_e32 v126, 16, v127
	v_and_b32_e32 v127, 0xffff0000, v127
	v_lshlrev_b32_e32 v128, 16, v129
	v_and_b32_e32 v129, 0xffff0000, v129
	v_pk_add_f32 v[126:127], v[126:127], v[128:129]
	v_lshlrev_b32_e32 v128, 16, v122
	v_pk_add_f32 v[46:47], v[126:127], v[46:47]
	v_lshlrev_b32_e32 v126, 16, v124
	v_and_b32_e32 v127, 0xffff0000, v124
	v_and_b32_e32 v129, 0xffff0000, v122
	v_pk_add_f32 v[186:187], v[186:187], v[188:189]
	v_pk_add_f32 v[126:127], v[126:127], v[128:129]
	v_pk_add_f32 v[44:45], v[186:187], v[44:45]
	v_pk_add_f32 v[40:41], v[126:127], v[40:41]
	v_lshlrev_b32_e32 v124, 16, v125
	v_and_b32_e32 v125, 0xffff0000, v125
	v_lshlrev_b32_e32 v122, 16, v123
	v_and_b32_e32 v123, 0xffff0000, v123
	v_pk_add_f32 v[122:123], v[124:125], v[122:123]
	v_mov_b32_e32 v124, v41
	v_mov_b32_e32 v125, v45
	v_pk_add_f32 v[42:43], v[122:123], v[42:43]
	v_mov_b32_e32 v122, v40
	v_mov_b32_e32 v123, v44
	v_pk_mul_f32 v[124:125], v[124:125], v[124:125]
	v_lshlrev_b32_e32 v126, 16, v120
	v_pk_fma_f32 v[122:123], v[122:123], v[122:123], v[124:125]
	v_mov_b32_e32 v124, v42
	v_mov_b32_e32 v125, v46
	v_pk_fma_f32 v[122:123], v[124:125], v[124:125], v[122:123]
	v_mov_b32_e32 v124, v43
	v_mov_b32_e32 v125, v47
	v_pk_fma_f32 v[122:123], v[124:125], v[124:125], v[122:123]
	v_lshlrev_b32_e32 v124, 16, v118
	v_and_b32_e32 v125, 0xffff0000, v118
	v_and_b32_e32 v127, 0xffff0000, v120
	v_lshlrev_b32_e32 v118, 16, v119
	v_and_b32_e32 v119, 0xffff0000, v119
	v_lshlrev_b32_e32 v120, 16, v121
	v_and_b32_e32 v121, 0xffff0000, v121
	v_pk_add_f32 v[118:119], v[118:119], v[120:121]
	v_lshlrev_b32_e32 v120, 16, v116
	v_pk_add_f32 v[38:39], v[118:119], v[38:39]
	v_lshlrev_b32_e32 v118, 16, v114
	v_and_b32_e32 v119, 0xffff0000, v114
	v_and_b32_e32 v121, 0xffff0000, v116
	v_pk_add_f32 v[118:119], v[118:119], v[120:121]
	v_pk_add_f32 v[124:125], v[124:125], v[126:127]
	v_pk_add_f32 v[118:119], v[118:119], v[32:33]
	v_lshlrev_b32_e32 v32, 16, v115
	v_and_b32_e32 v33, 0xffff0000, v115
	v_lshlrev_b32_e32 v114, 16, v117
	v_and_b32_e32 v115, 0xffff0000, v117
	v_pk_add_f32 v[36:37], v[124:125], v[36:37]
	v_pk_add_f32 v[32:33], v[32:33], v[114:115]
	v_lshlrev_b32_e32 v144, 16, v145
	v_pk_add_f32 v[114:115], v[32:33], v[34:35]
	v_mov_b32_e32 v34, v119
	v_mov_b32_e32 v35, v37
	v_and_b32_e32 v145, 0xffff0000, v145
	v_lshlrev_b32_e32 v146, 16, v147
	v_and_b32_e32 v147, 0xffff0000, v147
	v_lshlrev_b32_e32 v138, 16, v139
	v_and_b32_e32 v139, 0xffff0000, v139
	v_lshlrev_b32_e32 v142, 16, v143
	v_and_b32_e32 v143, 0xffff0000, v143
	v_mov_b32_e32 v32, v118
	v_mov_b32_e32 v33, v36
	v_pk_mul_f32 v[34:35], v[34:35], v[34:35]
	v_pk_add_f32 v[144:145], v[144:145], v[146:147]
	v_pk_add_f32 v[138:139], v[138:139], v[142:143]
	v_pk_fma_f32 v[32:33], v[32:33], v[32:33], v[34:35]
	v_mov_b32_e32 v34, v114
	v_mov_b32_e32 v35, v38
	v_pk_add_f32 v[62:63], v[144:145], v[62:63]
	v_pk_mul_f32 v[144:145], v[60:61], v[60:61]
	v_pk_add_f32 v[58:59], v[138:139], v[58:59]
	v_pk_mul_f32 v[138:139], v[56:57], v[56:57]
	v_pk_fma_f32 v[32:33], v[34:35], v[34:35], v[32:33]
	v_mov_b32_e32 v34, v115
	v_mov_b32_e32 v35, v39
	v_pk_mul_f32 v[146:147], v[62:63], v[62:63]
	v_pk_mul_f32 v[142:143], v[58:59], v[58:59]
	v_lshlrev_b32_e32 v134, 16, v135
	v_and_b32_e32 v135, 0xffff0000, v135
	v_lshlrev_b32_e32 v136, 16, v137
	v_and_b32_e32 v137, 0xffff0000, v137
	v_pk_fma_f32 v[32:33], v[34:35], v[34:35], v[32:33]
	v_add_f32_e32 v34, v138, v139
	v_add_f32_e32 v35, v144, v145
	v_pk_add_f32 v[134:135], v[134:135], v[136:137]
	v_add_f32_e32 v34, v142, v34
	v_add_f32_e32 v35, v146, v35
	v_pk_add_f32 v[54:55], v[134:135], v[54:55]
	v_pk_mul_f32 v[134:135], v[52:53], v[52:53]
	v_add_f32_e32 v34, v143, v34
	v_add_f32_e32 v35, v147, v35
	v_pk_mul_f32 v[136:137], v[54:55], v[54:55]
	v_lshlrev_b32_e32 v130, 16, v131
	v_and_b32_e32 v131, 0xffff0000, v131
	v_lshlrev_b32_e32 v132, 16, v133
	v_and_b32_e32 v133, 0xffff0000, v133
	v_add_f32_e32 v34, v35, v34
	v_add_f32_e32 v35, v134, v135
	v_pk_add_f32 v[130:131], v[130:131], v[132:133]
	v_add_f32_e32 v35, v136, v35
	v_pk_add_f32 v[50:51], v[130:131], v[50:51]
	v_pk_mul_f32 v[130:131], v[48:49], v[48:49]
	v_add_f32_e32 v35, v137, v35
	v_pk_mul_f32 v[132:133], v[50:51], v[50:51]
	v_add_f32_e32 v34, v35, v34
	v_add_f32_e32 v35, v130, v131
	v_add_f32_e32 v35, v132, v35
	v_add_f32_e32 v35, v133, v35
	v_add_f32_e32 v34, v35, v34
	v_add_f32_e32 v34, v123, v34
	v_add_f32_e32 v34, v122, v34
	v_add_f32_e32 v33, v33, v34
	v_add_f32_e32 v32, v32, v33
	ds_bpermute_b32 v33, v97, v32
	v_lshl_add_u64 v[112:113], v[112:113], 0, s[8:9]
	s_waitcnt vmcnt(0)
; __device__ __forceinline__ unsigned cvt_pk_bf16(float lo, float hi) { unsigned r; asm volatile("v_cvt_pk_bf16_f32 %0, %1, %2" : "=v"(r) : "v"(lo), "v"(hi)); return r; }
; __device__ __forceinline__ void norm_phase(const float* lat, const float* ctxp, const bf16_t* dbuf, const bf16_t* dbuf2, const bf16_t* dpart, float* xout, int nrows, const float* gw, const float* mod, int shift_off, int scale_off, bf16_t* outb, float* outf) {
;     ...
;         const int b = row < ML ? (row >> 12) : 8;
;         if (b != cur_b) {
;             cur_b = b;
; #pragma unroll
;             for (int i = 0; i < 8; ++i) { const int col = i * 256 + lane * 4; ca[i] = *(const f32x4*)(gw + col); cb[i] = (f32x4){0.f, 0.f, 0.f, 0.f};
;                 if (mod) { const f32x4 sc = *(const f32x4*)(mod + (size_t)b * NMODC + scale_off + col); cb[i] = *(const f32x4*)(mod + (size_t)b * NMODC + shift_off + col); ca[i] = ca[i] * (sc + 1.f); } }
;     ...
;         ss = wave_sum(ss);
;         const float rstd = rsqrtf(ss * (1.f / 2048.f) + 1e-6f);
; #pragma unroll
;         for (int i = 0; i < 8; ++i) {
;             const int col = i * 256 + lane * 4;
;             if (xout && row < ML) __builtin_nontemporal_store(v[i], (f32x4*)(xout + (size_t)row * D + col));
;             const f32x4 y = v[i] * rstd * ca[i] + cb[i];
;             if (outb) { u32x2 o; o.x = cvt_pk_bf16(y[0], y[1]); o.y = cvt_pk_bf16(y[2], y[3]); *(u32x2*)(outb + (size_t)row * D + col) = o; }
;             else __builtin_nontemporal_store(y, (f32x4*)(outf + (size_t)row * D + col));
;         }
; #pragma unroll
;         for (int i = 0; i < 8; ++i) { v[i] = nv[i]; dv[i] = nd[i]; dw[i] = nw2[i]; }
	v_mov_b64_e32 v[124:125], v[164:165]
	v_mov_b64_e32 v[126:127], v[162:163]
	v_mov_b64_e32 v[130:131], v[152:153]
	s_waitcnt lgkmcnt(0)
	v_add_f32_e32 v32, v32, v33
	ds_bpermute_b32 v33, v179, v32
	v_mov_b64_e32 v[134:135], v[150:151]
	v_mov_b64_e32 v[138:139], v[148:149]
	v_mov_b64_e32 v[144:145], v[140:141]
	v_mov_b64_e32 v[120:121], v[174:175]
	s_waitcnt lgkmcnt(0)
	v_add_f32_e32 v32, v32, v33
	ds_bpermute_b32 v33, v180, v32
	v_mov_b64_e32 v[122:123], v[172:173]
	v_mov_b64_e32 v[128:129], v[170:171]
	v_mov_b64_e32 v[132:133], v[160:161]
	v_mov_b64_e32 v[136:137], v[158:159]
	s_waitcnt lgkmcnt(0)
	v_add_f32_e32 v32, v32, v33
	ds_bpermute_b32 v33, v182, v32
	v_mov_b64_e32 v[142:143], v[156:157]
	v_mov_b64_e32 v[146:147], v[154:155]
	s_waitcnt lgkmcnt(0)
	v_add_f32_e32 v32, v32, v33
	ds_bpermute_b32 v33, v183, v32
	s_waitcnt lgkmcnt(0)
	v_add_f32_e32 v32, v32, v33
	ds_bpermute_b32 v33, v184, v32
	s_waitcnt lgkmcnt(0)
	v_add_f32_e32 v32, v32, v33
	v_fmamk_f32 v32, v32, 0x3a000000, v185
	v_mul_f32_e32 v33, 0x4b800000, v32
	v_cmp_gt_f32_e32 vcc, s11, v32
	s_nop 1
	v_cndmask_b32_e32 v32, v32, v33, vcc
	v_rsq_f32_e32 v32, v32
	s_nop 0
	v_mul_f32_e32 v33, 0x45800000, v32
	v_cndmask_b32_e32 v116, v32, v33, vcc
	v_pk_mul_f32 v[32:33], v[60:61], v[116:117] op_sel_hi:[1,0]
	v_pk_mul_f32 v[34:35], v[62:63], v[116:117] op_sel_hi:[1,0]
	v_pk_fma_f32 v[32:33], v[28:29], v[32:33], 0 op_sel_hi:[1,1,0]
	v_pk_fma_f32 v[34:35], v[30:31], v[34:35], 0 op_sel_hi:[1,1,0]
	global_store_dwordx4 v[110:111], v[32:35], off nt
	v_mov_b32_e32 v60, v88
	v_mov_b32_e32 v61, v89
	v_pk_mul_f32 v[32:33], v[56:57], v[116:117] op_sel_hi:[1,0]
	v_pk_mul_f32 v[34:35], v[58:59], v[116:117] op_sel_hi:[1,0]
	v_pk_fma_f32 v[32:33], v[24:25], v[32:33], 0 op_sel_hi:[1,1,0]
	v_pk_fma_f32 v[34:35], v[26:27], v[34:35], 0 op_sel_hi:[1,1,0]
	global_store_dwordx4 v[110:111], v[32:35], off offset:1024 nt
	v_mov_b32_e32 v62, v90
	v_mov_b32_e32 v63, v91
	v_pk_mul_f32 v[32:33], v[52:53], v[116:117] op_sel_hi:[1,0]
	v_pk_mul_f32 v[34:35], v[54:55], v[116:117] op_sel_hi:[1,0]
	v_pk_fma_f32 v[32:33], v[20:21], v[32:33], 0 op_sel_hi:[1,1,0]
	v_pk_fma_f32 v[34:35], v[22:23], v[34:35], 0 op_sel_hi:[1,1,0]
	global_store_dwordx4 v[110:111], v[32:35], off offset:2048 nt
	v_mov_b32_e32 v56, v80
	v_mov_b32_e32 v57, v81
	v_pk_mul_f32 v[32:33], v[48:49], v[116:117] op_sel_hi:[1,0]
	v_pk_mul_f32 v[34:35], v[50:51], v[116:117] op_sel_hi:[1,0]
	v_pk_fma_f32 v[32:33], v[16:17], v[32:33], 0 op_sel_hi:[1,1,0]
	v_pk_fma_f32 v[34:35], v[18:19], v[34:35], 0 op_sel_hi:[1,1,0]
	global_store_dwordx4 v[110:111], v[32:35], off offset:3072 nt
	v_mov_b32_e32 v58, v82
	v_mov_b32_e32 v59, v83
	v_pk_mul_f32 v[32:33], v[44:45], v[116:117] op_sel_hi:[1,0]
	v_pk_mul_f32 v[34:35], v[46:47], v[116:117] op_sel_hi:[1,0]
	v_add_co_u32_e32 v44, vcc, s10, v110
	v_pk_fma_f32 v[34:35], v[14:15], v[34:35], 0 op_sel_hi:[1,1,0]
	v_pk_fma_f32 v[32:33], v[12:13], v[32:33], 0 op_sel_hi:[1,1,0]
	v_addc_co_u32_e32 v45, vcc, 0, v111, vcc
	global_store_dwordx4 v[44:45], v[32:35], off nt
	v_lshl_add_u64 v[110:111], v[110:111], 0, s[6:7]
	v_mov_b32_e32 v52, v84
	v_pk_mul_f32 v[32:33], v[40:41], v[116:117] op_sel_hi:[1,0]
	v_pk_mul_f32 v[34:35], v[42:43], v[116:117] op_sel_hi:[1,0]
	v_pk_fma_f32 v[32:33], v[8:9], v[32:33], 0 op_sel_hi:[1,1,0]
	v_pk_fma_f32 v[34:35], v[10:11], v[34:35], 0 op_sel_hi:[1,1,0]
	global_store_dwordx4 v[44:45], v[32:35], off offset:1024 nt
	v_mov_b32_e32 v53, v85
	v_mov_b32_e32 v54, v86
	v_pk_mul_f32 v[32:33], v[36:37], v[116:117] op_sel_hi:[1,0]
	v_pk_mul_f32 v[34:35], v[38:39], v[116:117] op_sel_hi:[1,0]
	v_pk_fma_f32 v[32:33], v[4:5], v[32:33], 0 op_sel_hi:[1,1,0]
	v_pk_fma_f32 v[34:35], v[6:7], v[34:35], 0 op_sel_hi:[1,1,0]
	global_store_dwordx4 v[44:45], v[32:35], off offset:2048 nt
	v_mov_b32_e32 v55, v87
	v_mov_b32_e32 v48, v72
	v_pk_mul_f32 v[32:33], v[118:119], v[116:117] op_sel_hi:[1,0]
	v_pk_mul_f32 v[34:35], v[114:115], v[116:117] op_sel_hi:[1,0]
	v_pk_fma_f32 v[32:33], v[0:1], v[32:33], 0 op_sel_hi:[1,1,0]
	v_pk_fma_f32 v[34:35], v[2:3], v[34:35], 0 op_sel_hi:[1,1,0]
	global_store_dwordx4 v[44:45], v[32:35], off offset:3072 nt
	v_mov_b64_e32 v[114:115], v[168:169]
	v_mov_b64_e32 v[118:119], v[166:167]
	v_mov_b64_e32 v[116:117], v[176:177]
	v_mov_b32_e32 v49, v73
	v_mov_b32_e32 v50, v74
	v_mov_b32_e32 v51, v75
	v_mov_b32_e32 v44, v92
	v_mov_b32_e32 v45, v93
	v_mov_b32_e32 v46, v94
	v_mov_b32_e32 v47, v95
	v_mov_b32_e32 v40, v76
	v_mov_b32_e32 v41, v77
	v_mov_b32_e32 v42, v78
	v_mov_b32_e32 v43, v79
	v_mov_b32_e32 v36, v68
	v_mov_b32_e32 v37, v69
	v_mov_b32_e32 v38, v70
	v_mov_b32_e32 v39, v71
	v_mov_b32_e32 v32, v64
	v_mov_b32_e32 v33, v65
	v_mov_b32_e32 v34, v66
	v_mov_b32_e32 v35, v67
	s_andn2_b64 exec, exec, s[4:5]
	s_cbranch_execz .LBB0_1897
.LBB0_1893:
	v_min_i32_e32 v64, 0x8000, v96
	v_ashrrev_i32_e32 v64, 12, v64
	v_cmp_ne_u32_e32 vcc, v64, v181
	s_and_saveexec_b64 s[0:1], vcc
	s_cbranch_execz .LBB0_1895
	global_load_dwordx4 v[28:31], v[100:101], off
	global_load_dwordx4 v[24:27], v[100:101], off offset:1024
	global_load_dwordx4 v[20:23], v[100:101], off offset:2048
	global_load_dwordx4 v[16:19], v[100:101], off offset:3072
	global_load_dwordx4 v[12:15], v[102:103], off
	global_load_dwordx4 v[8:11], v[104:105], off
	global_load_dwordx4 v[4:7], v[106:107], off
	global_load_dwordx4 v[0:3], v[108:109], off
	v_mov_b32_e32 v181, v64
	s_waitcnt vmcnt(0)
